# RG-LRU scan rewrite: gate biases folded into the MFMA accumulator init, image read-modify-write only in the second half of the scan, lgkmcnt kept below 16 outstanding
# speedup vs baseline: 1.0363x; 1.0086x over previous
.LBB0_598:
	s_lshl_b32 s4, s84, 5
	s_and_b32 s68, s4, 32
	s_bfe_u32 s70, s84, 0x40001
	s_or_b32 s34, s68, s3
	s_lshl_b32 s67, s70, 6
	v_or_b32_e32 v164, s34, v3
	v_or_b32_e32 v4, s67, v164
	v_lshlrev_b32_e32 v128, 2, v4
	v_lshl_add_u64 v[134:135], s[90:91], 0, v[128:129]
	v_add_co_u32_e32 v4, vcc, s53, v134
	s_ashr_i32 s69, s84, 5
	s_nop 0
	v_addc_co_u32_e32 v5, vcc, 0, v135, vcc
	v_add_co_u32_e32 v6, vcc, s55, v134
	s_lshl_b32 s4, s69, 4
	s_nop 0
	v_addc_co_u32_e32 v7, vcc, 0, v135, vcc
	global_load_dword v8, v[4:5], off offset:576
	global_load_dword v9, v[6:7], off offset:576
	v_add_co_u32_e32 v4, vcc, s56, v134
	s_or_b32 s4, s4, s70
	s_nop 0
	v_addc_co_u32_e32 v5, vcc, 0, v135, vcc
	v_add_co_u32_e32 v6, vcc, s57, v134
	s_mul_i32 s28, s4, 0x804
	s_nop 0
	v_addc_co_u32_e32 v7, vcc, 0, v135, vcc
	global_load_dword v10, v[4:5], off offset:576
	s_nop 0
	global_load_dword v6, v[6:7], off offset:576
	v_add_co_u32_e32 v4, vcc, 0xd000, v134
	s_ashr_i32 s29, s28, 31
	s_nop 0
	v_addc_co_u32_e32 v5, vcc, 0, v135, vcc
	global_load_dword v133, v[4:5], off offset:576
	s_lshl_b64 s[28:29], s[28:29], 7
	s_add_u32 s50, s42, s28
	s_addc_u32 s51, s43, s29
	s_bitcmp1_b32 s84, 0
	s_cselect_b64 s[28:29], -1, 0
	s_mov_b64 s[26:27], -1
	s_lshl_b32 s71, s70, 10
	s_and_b64 vcc, exec, s[28:29]
	s_waitcnt vmcnt(4)
	v_bfe_u32 v4, v8, 16, 1
	v_add3_u32 v184, v8, v4, s54
	s_waitcnt vmcnt(3)
	v_bfe_u32 v5, v9, 16, 1
	v_add3_u32 v185, v9, v5, s54
	s_waitcnt vmcnt(2)
	v_bfe_u32 v4, v10, 16, 1
	v_add3_u32 v195, v10, v4, s54
	s_waitcnt vmcnt(1)
	v_bfe_u32 v4, v6, 16, 1
	v_add3_u32 v197, v6, v4, s54
	s_waitcnt vmcnt(0)
	s_cmpk_gt_u32 s85, 0xff
	s_cbranch_scc1 .Lrec2_bwd
	v_and_b32_e32 v252, 15, v157
	v_lshrrev_b32_e32 v253, 4, v157
	s_bfe_u32 s5, s85, 0x10006
	s_bfe_u32 s6, s85, 0x10007
	s_and_b32 s8, s84, 1
	v_readlane_b32 s26, v254, 13
	v_readlane_b32 s27, v254, 14
	s_nop 3
	s_lshl_b32 s9, s70, 2
	s_lshl_b32 s52, s9, 15
	s_add_u32 s26, s26, 0x100000
	s_addc_u32 s27, s27, 0
	s_add_u32 s26, s26, s52
	s_addc_u32 s27, s27, 0
	v_add_u32_e32 v8, s34, v252
	v_lshlrev_b32_e32 v9, 7, v8
	v_lshl_add_u32 v9, v253, 4, v9
	s_lshl_b32 s64, s8, 6
	s_xor_b32 s71, s64, 64
	v_add_u32_e32 v10, s64, v9
	v_add_u32_e32 v255, s71, v9
	s_add_u32 s38, s26, 0x0
	s_addc_u32 s39, s27, 0
	global_load_dwordx4 v[20:23], v10, s[38:39]
	global_load_dwordx4 v[24:27], v255, s[38:39]
	s_add_u32 s38, s26, 0x2000
	s_addc_u32 s39, s27, 0
	global_load_dwordx4 v[28:31], v10, s[38:39]
	global_load_dwordx4 v[32:35], v255, s[38:39]
	s_add_u32 s38, s26, 0x4000
	s_addc_u32 s39, s27, 0
	global_load_dwordx4 v[36:39], v10, s[38:39]
	global_load_dwordx4 v[40:43], v255, s[38:39]
	s_add_u32 s38, s26, 0x6000
	s_addc_u32 s39, s27, 0
	global_load_dwordx4 v[44:47], v10, s[38:39]
	global_load_dwordx4 v[48:51], v255, s[38:39]
	s_add_u32 s38, s26, 0x8000
	s_addc_u32 s39, s27, 0
	global_load_dwordx4 v[52:55], v10, s[38:39]
	global_load_dwordx4 v[56:59], v255, s[38:39]
	s_add_u32 s38, s26, 0xa000
	s_addc_u32 s39, s27, 0
	global_load_dwordx4 v[60:63], v10, s[38:39]
	global_load_dwordx4 v[64:67], v255, s[38:39]
	s_add_u32 s38, s26, 0xc000
	s_addc_u32 s39, s27, 0
	global_load_dwordx4 v[68:71], v10, s[38:39]
	global_load_dwordx4 v[72:75], v255, s[38:39]
	s_add_u32 s38, s26, 0xe000
	s_addc_u32 s39, s27, 0
	global_load_dwordx4 v[76:79], v10, s[38:39]
	global_load_dwordx4 v[80:83], v255, s[38:39]
	s_lshl_b32 s52, s9, 8
	s_add_i32 s52, s52, 0x15240
	v_lshlrev_b32_e32 v8, 2, v8
	v_add_u32_e32 v9, s52, v8
	global_load_dword v128, v9, s[90:91]
	global_load_dword v178, v9, s[90:91] offset:256
	s_lshl_b32 s52, s70, 8
	s_add_i32 s52, s52, 0x12240
	v_add_u32_e32 v9, s52, v8
	global_load_dword v179, v9, s[90:91]
	v_lshlrev_b32_e32 v198, 3, v253
	v_sub_u32_e32 v198, v252, v198
	v_lshl_add_u32 v198, s6, 4, v198
	v_cmp_gt_u32_e32 vcc, 8, v198
	v_and_b32_e32 v199, 1, v198
	v_lshlrev_b32_e32 v199, 4, v199
	v_lshrrev_b32_e32 v200, 1, v198
	s_nop 1
	v_cndmask_b32_e32 v200, 7, v200, vcc
	v_cmp_eq_u32_e64 s[58:59], 0, v200
	v_cmp_eq_u32_e64 s[60:61], 1, v200
	v_cmp_eq_u32_e64 s[98:99], 2, v200
	v_cmp_eq_u32_e64 s[100:101], 3, v200
	s_nop 1
	v_lshrrev_b32_e32 v201, 16, v184
	v_lshlrev_b32_e32 v201, v199, v201
	v_cndmask_b32_e64 v84, 0, v201, s[58:59]
	v_cndmask_b32_e64 v85, 0, v201, s[60:61]
	v_cndmask_b32_e64 v86, 0, v201, s[98:99]
	v_cndmask_b32_e64 v87, 0, v201, s[100:101]
	v_lshrrev_b32_e32 v201, 16, v185
	v_lshlrev_b32_e32 v201, v199, v201
	v_cndmask_b32_e64 v88, 0, v201, s[58:59]
	v_cndmask_b32_e64 v89, 0, v201, s[60:61]
	v_cndmask_b32_e64 v90, 0, v201, s[98:99]
	v_cndmask_b32_e64 v91, 0, v201, s[100:101]
	v_lshrrev_b32_e32 v201, 16, v195
	v_lshlrev_b32_e32 v201, v199, v201
	v_cndmask_b32_e64 v92, 0, v201, s[58:59]
	v_cndmask_b32_e64 v93, 0, v201, s[60:61]
	v_cndmask_b32_e64 v94, 0, v201, s[98:99]
	v_cndmask_b32_e64 v95, 0, v201, s[100:101]
	v_lshrrev_b32_e32 v201, 16, v197
	v_lshlrev_b32_e32 v201, v199, v201
	v_cndmask_b32_e64 v96, 0, v201, s[58:59]
	v_cndmask_b32_e64 v97, 0, v201, s[60:61]
	v_cndmask_b32_e64 v98, 0, v201, s[98:99]
	v_cndmask_b32_e64 v99, 0, v201, s[100:101]
	v_mov_b32_e32 v184, 1.0
	v_mov_b32_e32 v185, 1.0
	v_lshrrev_b32_e32 v8, 2, v252
	v_and_b32_e32 v9, 3, v252
	v_lshl_add_u32 v8, v8, 3, v9
	v_lshl_add_u32 v8, s5, 5, v8
	v_mul_u32_u24_e32 v8, 0x90, v8
	v_lshl_add_u32 v8, v253, 4, v8
	v_add_u32_e32 v8, 0x20900, v8
	v_add_u32_e32 v130, s64, v8
	v_add_u32_e32 v131, s71, v8
	v_and_b32_e32 v8, 0xff, v156
	v_lshrrev_b32_e32 v9, 3, v8
	v_mul_u32_u24_e32 v9, 0x90, v9
	v_and_b32_e32 v10, 7, v8
	v_lshl_add_u32 v9, v10, 4, v9
	v_add_u32_e32 v134, 0x20900, v9
	v_lshlrev_b32_e32 v154, 4, v8
	v_add_u32_e32 v155, 0x1000, v154
	v_min_u32_e32 v9, 23, v8
	v_add_u32_e32 v9, 0x200, v9
	v_lshlrev_b32_e32 v159, 4, v9
	v_lshrrev_b32_e32 v10, 3, v9
	v_mul_u32_u24_e32 v10, 0x90, v10
	v_and_b32_e32 v9, 7, v9
	v_lshl_add_u32 v10, v9, 4, v10
	v_add_u32_e32 v135, 0x20900, v10
	s_lshl_b32 s52, s6, 8
	s_add_i32 s52, s52, 0x20100
	v_lshl_add_u32 v183, v252, 3, s52
	s_lshl_b32 s52, s5, 7
	v_add_u32_e32 v182, s52, v183
	s_lshl_b32 s52, s5, 11
	s_lshl_b32 s9, s6, 5
	s_add_i32 s52, s52, s9
	s_add_i32 s52, s52, 0x100
	v_lshlrev_b32_e32 v8, 9, v253
	v_lshl_add_u32 v8, v252, 1, v8
	v_add_u32_e32 v116, s52, v8
	v_lshlrev_b32_e32 v117, 2, v252
	v_cmp_eq_u32_e64 s[10:11], 0, v253
	v_cmp_lt_u32_e64 s[16:17], 0, v253
	v_cmp_lt_u32_e64 s[20:21], 1, v253
	v_cmp_lt_u32_e64 s[22:23], 2, v253
	s_cmp_lg_u32 s5, 0
	s_cselect_b64 s[24:25], -1, 0
	v_mov_b32_e32 v180, 0
	s_add_u32 s26, s50, 0x0
	s_addc_u32 s27, s51, 0
	global_load_dwordx4 v[230:233], v154, s[26:27]
	global_load_dwordx4 v[234:237], v155, s[26:27]
	global_load_dwordx4 v[238:241], v159, s[26:27]
	s_add_u32 s26, s50, 0x2000
	s_addc_u32 s27, s51, 0
	global_load_dwordx4 v[146:149], v154, s[26:27]
	global_load_dwordx4 v[150:153], v155, s[26:27]
	global_load_dwordx4 v[160:163], v159, s[26:27]
	s_waitcnt vmcnt(0)
	v_mov_b32_e32 v12, v128
	v_mov_b32_e32 v16, v178
	v_mov_b32_e32 v242, v133
	v_mov_b32_e32 v13, v128
	v_mov_b32_e32 v17, v178
	v_mov_b32_e32 v243, v133
	v_mov_b32_e32 v14, v128
	v_mov_b32_e32 v18, v178
	v_mov_b32_e32 v244, v133
	v_mov_b32_e32 v15, v128
	v_mov_b32_e32 v19, v178
	v_mov_b32_e32 v245, v133
	ds_write_b128 v134, v[230:233]
	ds_write_b128 v134, v[234:237] offset:4608
	ds_write_b128 v135, v[238:241]
	s_add_u32 s26, s50, 0x4000
	s_addc_u32 s27, s51, 0
	global_load_dwordx4 v[230:233], v154, s[26:27]
	global_load_dwordx4 v[234:237], v155, s[26:27]
	global_load_dwordx4 v[238:241], v159, s[26:27]
	s_mov_b32 s4, 0
	s_waitcnt lgkmcnt(0)
	s_barrier
.Lrec2_loop_d0:
	ds_read_b128 v[198:201], v130 offset:0
	ds_read_b128 v[214:217], v130 offset:576
	ds_read_b128 v[202:205], v131 offset:0
	ds_read_b128 v[218:221], v131 offset:576
	ds_read_b128 v[206:209], v130 offset:144
	ds_read_b128 v[222:225], v130 offset:720
	ds_read_b128 v[210:213], v131 offset:144
	s_waitcnt lgkmcnt(14)
	ds_read_b128 v[226:229], v131 offset:720
	s_waitcnt lgkmcnt(6)
	v_mfma_f32_16x16x32_bf16 v[100:103], v[198:201], v[20:23], v[12:15]
	v_mfma_f32_16x16x32_bf16 v[104:107], v[198:201], v[52:55], v[16:19]
	v_mfma_f32_16x16x32_bf16 v[108:111], v[198:201], v[84:87], v[242:245]
	v_mfma_f32_16x16x32_bf16 v[112:115], v[214:217], v[20:23], v[12:15]
	v_mfma_f32_16x16x32_bf16 v[138:141], v[214:217], v[52:55], v[16:19]
	v_mfma_f32_16x16x32_bf16 v[142:145], v[214:217], v[84:87], v[242:245]
	s_waitcnt lgkmcnt(4)
	v_mfma_f32_16x16x32_bf16 v[100:103], v[202:205], v[24:27], v[100:103]
	v_mfma_f32_16x16x32_bf16 v[104:107], v[202:205], v[56:59], v[104:107]
	v_mfma_f32_16x16x32_bf16 v[112:115], v[218:221], v[24:27], v[112:115]
	v_mfma_f32_16x16x32_bf16 v[138:141], v[218:221], v[56:59], v[138:141]
	ds_read_b128 v[198:201], v130 offset:288
	ds_read_b128 v[214:217], v130 offset:864
	ds_read_b128 v[202:205], v131 offset:288
	ds_read_b128 v[218:221], v131 offset:864
	s_waitcnt lgkmcnt(6)
	v_mfma_f32_16x16x32_bf16 v[100:103], v[206:209], v[28:31], v[100:103]
	v_mfma_f32_16x16x32_bf16 v[104:107], v[206:209], v[60:63], v[104:107]
	v_mfma_f32_16x16x32_bf16 v[108:111], v[206:209], v[88:91], v[108:111]
	v_mfma_f32_16x16x32_bf16 v[112:115], v[222:225], v[28:31], v[112:115]
	v_mfma_f32_16x16x32_bf16 v[138:141], v[222:225], v[60:63], v[138:141]
	v_mfma_f32_16x16x32_bf16 v[142:145], v[222:225], v[88:91], v[142:145]
	s_waitcnt lgkmcnt(4)
	v_mfma_f32_16x16x32_bf16 v[100:103], v[210:213], v[32:35], v[100:103]
	v_mfma_f32_16x16x32_bf16 v[104:107], v[210:213], v[64:67], v[104:107]
	v_mfma_f32_16x16x32_bf16 v[112:115], v[226:229], v[32:35], v[112:115]
	v_mfma_f32_16x16x32_bf16 v[138:141], v[226:229], v[64:67], v[138:141]
	ds_read_b128 v[206:209], v130 offset:432
	ds_read_b128 v[222:225], v130 offset:1008
	ds_read_b128 v[210:213], v131 offset:432
	ds_read_b128 v[226:229], v131 offset:1008
	s_waitcnt lgkmcnt(6)
	v_mfma_f32_16x16x32_bf16 v[100:103], v[198:201], v[36:39], v[100:103]
	v_mfma_f32_16x16x32_bf16 v[104:107], v[198:201], v[68:71], v[104:107]
	v_mfma_f32_16x16x32_bf16 v[108:111], v[198:201], v[92:95], v[108:111]
	v_mfma_f32_16x16x32_bf16 v[112:115], v[214:217], v[36:39], v[112:115]
	v_mfma_f32_16x16x32_bf16 v[138:141], v[214:217], v[68:71], v[138:141]
	v_mfma_f32_16x16x32_bf16 v[142:145], v[214:217], v[92:95], v[142:145]
	s_waitcnt lgkmcnt(4)
	v_mfma_f32_16x16x32_bf16 v[100:103], v[202:205], v[40:43], v[100:103]
	v_mfma_f32_16x16x32_bf16 v[104:107], v[202:205], v[72:75], v[104:107]
	v_mfma_f32_16x16x32_bf16 v[112:115], v[218:221], v[40:43], v[112:115]
	v_mfma_f32_16x16x32_bf16 v[138:141], v[218:221], v[72:75], v[138:141]
	s_waitcnt lgkmcnt(2)
	v_mfma_f32_16x16x32_bf16 v[100:103], v[206:209], v[44:47], v[100:103]
	v_mfma_f32_16x16x32_bf16 v[104:107], v[206:209], v[76:79], v[104:107]
	v_mfma_f32_16x16x32_bf16 v[108:111], v[206:209], v[96:99], v[108:111]
	v_mfma_f32_16x16x32_bf16 v[112:115], v[222:225], v[44:47], v[112:115]
	v_mfma_f32_16x16x32_bf16 v[138:141], v[222:225], v[76:79], v[138:141]
	v_mfma_f32_16x16x32_bf16 v[142:145], v[222:225], v[96:99], v[142:145]
	s_waitcnt lgkmcnt(0)
	v_mfma_f32_16x16x32_bf16 v[100:103], v[210:213], v[48:51], v[100:103]
	v_mfma_f32_16x16x32_bf16 v[104:107], v[210:213], v[80:83], v[104:107]
	v_mfma_f32_16x16x32_bf16 v[112:115], v[226:229], v[48:51], v[112:115]
	v_mfma_f32_16x16x32_bf16 v[138:141], v[226:229], v[80:83], v[138:141]
	s_waitcnt lgkmcnt(0)
	s_barrier
	s_waitcnt vmcnt(3)
	ds_write_b128 v134, v[146:149]
	ds_write_b128 v134, v[150:153] offset:4608
	ds_write_b128 v135, v[160:163]
	s_add_i32 s52, s4, 3
	s_min_u32 s52, s52, 31
	s_lshl_b32 s52, s52, 13
	s_add_u32 s26, s50, s52
	s_addc_u32 s27, s51, 0
	global_load_dwordx4 v[146:149], v154, s[26:27]
	global_load_dwordx4 v[150:153], v155, s[26:27]
	global_load_dwordx4 v[160:163], v159, s[26:27]
	v_exp_f32_e32 v198, v100
	v_exp_f32_e32 v199, v101
	v_exp_f32_e32 v200, v102
	v_exp_f32_e32 v201, v103
	v_exp_f32_e32 v202, v112
	v_exp_f32_e32 v203, v113
	v_exp_f32_e32 v204, v114
	v_exp_f32_e32 v205, v115
	v_exp_f32_e32 v214, v104
	v_add_f32_e32 v198, 1.0, v198
	v_exp_f32_e32 v215, v105
	v_add_f32_e32 v199, 1.0, v199
	v_exp_f32_e32 v216, v106
	v_add_f32_e32 v200, 1.0, v200
	v_exp_f32_e32 v217, v107
	v_add_f32_e32 v201, 1.0, v201
	v_exp_f32_e32 v218, v138
	v_add_f32_e32 v202, 1.0, v202
	v_exp_f32_e32 v219, v139
	v_add_f32_e32 v203, 1.0, v203
	v_exp_f32_e32 v220, v140
	v_add_f32_e32 v204, 1.0, v204
	v_exp_f32_e32 v221, v141
	v_add_f32_e32 v205, 1.0, v205
	v_rcp_f32_e32 v198, v198
	v_add_f32_e32 v214, 1.0, v214
	v_rcp_f32_e32 v199, v199
	v_add_f32_e32 v215, 1.0, v215
	v_rcp_f32_e32 v200, v200
	v_add_f32_e32 v216, 1.0, v216
	v_rcp_f32_e32 v201, v201
	v_add_f32_e32 v217, 1.0, v217
	v_rcp_f32_e32 v202, v202
	v_add_f32_e32 v218, 1.0, v218
	v_rcp_f32_e32 v203, v203
	v_add_f32_e32 v219, 1.0, v219
	v_rcp_f32_e32 v204, v204
	v_add_f32_e32 v220, 1.0, v220
	v_rcp_f32_e32 v205, v205
	v_add_f32_e32 v221, 1.0, v221
	v_mul_f32_e32 v198, v179, v198
	v_mul_f32_e32 v199, v179, v199
	v_mul_f32_e32 v200, v179, v200
	v_mul_f32_e32 v201, v179, v201
	v_mul_f32_e32 v202, v179, v202
	v_mul_f32_e32 v203, v179, v203
	v_mul_f32_e32 v204, v179, v204
	v_mul_f32_e32 v205, v179, v205
	v_exp_f32_e32 v120, v198
	v_exp_f32_e32 v121, v199
	v_exp_f32_e32 v122, v200
	v_exp_f32_e32 v123, v201
	v_exp_f32_e32 v124, v202
	v_exp_f32_e32 v125, v203
	v_exp_f32_e32 v126, v204
	v_exp_f32_e32 v127, v205
	v_fma_f32 v206, -v120, v120, 1.0
	v_fma_f32 v207, -v121, v121, 1.0
	v_fma_f32 v208, -v122, v122, 1.0
	v_fma_f32 v209, -v123, v123, 1.0
	v_fma_f32 v210, -v124, v124, 1.0
	v_fma_f32 v211, -v125, v125, 1.0
	v_fma_f32 v212, -v126, v126, 1.0
	v_fma_f32 v213, -v127, v127, 1.0
	v_max_f32_e32 v206, 0xda24260, v206
	v_max_f32_e32 v207, 0xda24260, v207
	v_max_f32_e32 v208, 0xda24260, v208
	v_max_f32_e32 v209, 0xda24260, v209
	v_max_f32_e32 v210, 0xda24260, v210
	v_max_f32_e32 v211, 0xda24260, v211
	v_max_f32_e32 v212, 0xda24260, v212
	v_max_f32_e32 v213, 0xda24260, v213
	v_mul_f32_e32 v198, v214, v206
	v_mul_f32_e32 v199, v215, v207
	v_mul_f32_e32 v200, v216, v208
	v_mul_f32_e32 v201, v217, v209
	v_mul_f32_e32 v202, v218, v210
	v_mul_f32_e32 v203, v219, v211
	v_mul_f32_e32 v204, v220, v212
	v_mul_f32_e32 v205, v221, v213
	v_mul_f32_e32 v214, v214, v198
	v_mul_f32_e32 v215, v215, v199
	v_mul_f32_e32 v216, v216, v200
	v_mul_f32_e32 v217, v217, v201
	v_mul_f32_e32 v218, v218, v202
	v_mul_f32_e32 v219, v219, v203
	v_mul_f32_e32 v220, v220, v204
	v_mul_f32_e32 v221, v221, v205
	v_rsq_f32_e32 v214, v214
	v_mul_f32_e32 v222, v108, v206
	v_rsq_f32_e32 v215, v215
	v_mul_f32_e32 v223, v109, v207
	v_rsq_f32_e32 v216, v216
	v_mul_f32_e32 v224, v110, v208
	v_rsq_f32_e32 v217, v217
	v_mul_f32_e32 v225, v111, v209
	v_rsq_f32_e32 v218, v218
	v_mul_f32_e32 v226, v142, v210
	v_rsq_f32_e32 v219, v219
	v_mul_f32_e32 v227, v143, v211
	v_rsq_f32_e32 v220, v220
	v_mul_f32_e32 v228, v144, v212
	v_rsq_f32_e32 v221, v221
	v_mul_f32_e32 v229, v145, v213
	v_mul_f32_e32 v170, v222, v214
	v_mul_f32_e32 v171, v223, v215
	v_mul_f32_e32 v172, v224, v216
	v_mul_f32_e32 v173, v225, v217
	v_mul_f32_e32 v174, v226, v218
	v_mul_f32_e32 v175, v227, v219
	v_mul_f32_e32 v176, v228, v220
	v_mul_f32_e32 v177, v229, v221
	v_mov_b32_e32 v198, v170
	v_mov_b32_e32 v199, v120
	v_fma_f32 v198, v121, v198, v171
	v_mul_f32_e32 v199, v199, v121
	v_fma_f32 v198, v122, v198, v172
	v_mul_f32_e32 v199, v199, v122
	v_fma_f32 v198, v123, v198, v173
	v_mul_f32_e32 v199, v199, v123
	v_fma_f32 v198, v124, v198, v174
	v_mul_f32_e32 v199, v199, v124
	v_fma_f32 v198, v125, v198, v175
	v_mul_f32_e32 v199, v199, v125
	v_fma_f32 v198, v126, v198, v176
	v_mul_f32_e32 v199, v199, v126
	v_fma_f32 v198, v127, v198, v177
	v_mul_f32_e32 v199, v199, v127
	ds_bpermute_b32 v164, v117, v199 offset:0
	ds_bpermute_b32 v246, v117, v198 offset:0
	ds_bpermute_b32 v165, v117, v199 offset:64
	ds_bpermute_b32 v247, v117, v198 offset:64
	ds_bpermute_b32 v166, v117, v199 offset:128
	ds_bpermute_b32 v248, v117, v198 offset:128
	ds_bpermute_b32 v167, v117, v199 offset:192
	ds_bpermute_b32 v249, v117, v198 offset:192
	s_waitcnt lgkmcnt(0)
	v_mov_b32_e32 v251, v246
	v_mov_b32_e32 v250, v164
	v_fma_f32 v251, v251, v165, v247
	v_mul_f32_e32 v250, v250, v165
	v_fma_f32 v251, v251, v166, v248
	v_mul_f32_e32 v250, v250, v166
	v_fma_f32 v251, v251, v167, v249
	v_mul_f32_e32 v250, v250, v167
	s_mov_b64 exec, s[10:11]
	ds_write_b64 v182, v[250:251] offset:0
	s_mov_b64 exec, -1
	s_waitcnt lgkmcnt(0)
	s_barrier
	ds_read2_b64 v[4:7], v183 offset0:0 offset1:16
	s_add_i32 s52, s4, 0
	s_lshl_b32 s52, s52, 12
	v_add_u32_e32 v197, s52, v116
	s_waitcnt lgkmcnt(0)
	v_fma_f32 v198, v180, v4, v5
	v_cndmask_b32_e64 v199, v180, v198, s[24:25]
	v_fma_f32 v180, v198, v6, v7
	v_fma_f32 v200, v199, v164, v246
	v_cndmask_b32_e64 v199, v199, v200, s[16:17]
	v_fma_f32 v200, v199, v165, v247
	v_cndmask_b32_e64 v199, v199, v200, s[20:21]
	v_fma_f32 v200, v199, v166, v248
	v_cndmask_b32_e64 v199, v199, v200, s[22:23]
	v_fma_f32 v214, v120, v199, v170
	v_fma_f32 v215, v121, v214, v171
	v_fma_f32 v216, v122, v215, v172
	v_fma_f32 v217, v123, v216, v173
	v_fma_f32 v218, v124, v217, v174
	v_fma_f32 v219, v125, v218, v175
	v_fma_f32 v220, v126, v219, v176
	v_fma_f32 v221, v127, v220, v177
	s_cmp_lt_u32 s4, 16
	s_cbranch_scc1 .Lrec2_rmw_d0_p0_store
	ds_read_u16 v206, v197 offset:0
	ds_read_u16 v207, v197 offset:64
	ds_read_u16 v208, v197 offset:128
	ds_read_u16 v209, v197 offset:192
	ds_read_u16 v210, v197 offset:256
	ds_read_u16 v211, v197 offset:320
	ds_read_u16 v212, v197 offset:384
	ds_read_u16 v213, v197 offset:448
	s_waitcnt lgkmcnt(0)
	v_lshlrev_b32_e32 v206, 16, v206
	v_lshlrev_b32_e32 v207, 16, v207
	v_lshlrev_b32_e32 v208, 16, v208
	v_lshlrev_b32_e32 v209, 16, v209
	v_lshlrev_b32_e32 v210, 16, v210
	v_lshlrev_b32_e32 v211, 16, v211
	v_lshlrev_b32_e32 v212, 16, v212
	v_lshlrev_b32_e32 v213, 16, v213
	v_add_f32_e32 v214, v214, v206
	v_add_f32_e32 v215, v215, v207
	v_add_f32_e32 v216, v216, v208
	v_add_f32_e32 v217, v217, v209
	v_add_f32_e32 v218, v218, v210
	v_add_f32_e32 v219, v219, v211
	v_add_f32_e32 v220, v220, v212
	v_add_f32_e32 v221, v221, v213
.Lrec2_rmw_d0_p0_store:
	v_cvt_pk_bf16_f32 v206, v214, v215
	v_cvt_pk_bf16_f32 v208, v216, v217
	v_cvt_pk_bf16_f32 v210, v218, v219
	v_cvt_pk_bf16_f32 v212, v220, v221
	ds_write_b16 v197, v206 offset:0
	ds_write_b16_d16_hi v197, v206 offset:64
	ds_write_b16 v197, v208 offset:128
	ds_write_b16_d16_hi v197, v208 offset:192
	ds_write_b16 v197, v210 offset:256
	ds_write_b16_d16_hi v197, v210 offset:320
	ds_write_b16 v197, v212 offset:384
	ds_write_b16_d16_hi v197, v212 offset:448
	ds_read_b128 v[198:201], v130 offset:0
	ds_read_b128 v[214:217], v130 offset:576
	ds_read_b128 v[202:205], v131 offset:0
	ds_read_b128 v[218:221], v131 offset:576
	ds_read_b128 v[206:209], v130 offset:144
	ds_read_b128 v[222:225], v130 offset:720
	ds_read_b128 v[210:213], v131 offset:144
	s_waitcnt lgkmcnt(14)
	ds_read_b128 v[226:229], v131 offset:720
	s_waitcnt lgkmcnt(6)
	v_mfma_f32_16x16x32_bf16 v[100:103], v[198:201], v[20:23], v[12:15]
	v_mfma_f32_16x16x32_bf16 v[104:107], v[198:201], v[52:55], v[16:19]
	v_mfma_f32_16x16x32_bf16 v[108:111], v[198:201], v[84:87], v[242:245]
	v_mfma_f32_16x16x32_bf16 v[112:115], v[214:217], v[20:23], v[12:15]
	v_mfma_f32_16x16x32_bf16 v[138:141], v[214:217], v[52:55], v[16:19]
	v_mfma_f32_16x16x32_bf16 v[142:145], v[214:217], v[84:87], v[242:245]
	s_waitcnt lgkmcnt(4)
	v_mfma_f32_16x16x32_bf16 v[100:103], v[202:205], v[24:27], v[100:103]
	v_mfma_f32_16x16x32_bf16 v[104:107], v[202:205], v[56:59], v[104:107]
	v_mfma_f32_16x16x32_bf16 v[112:115], v[218:221], v[24:27], v[112:115]
	v_mfma_f32_16x16x32_bf16 v[138:141], v[218:221], v[56:59], v[138:141]
	ds_read_b128 v[198:201], v130 offset:288
	ds_read_b128 v[214:217], v130 offset:864
	ds_read_b128 v[202:205], v131 offset:288
	ds_read_b128 v[218:221], v131 offset:864
	s_waitcnt lgkmcnt(6)
	v_mfma_f32_16x16x32_bf16 v[100:103], v[206:209], v[28:31], v[100:103]
	v_mfma_f32_16x16x32_bf16 v[104:107], v[206:209], v[60:63], v[104:107]
	v_mfma_f32_16x16x32_bf16 v[108:111], v[206:209], v[88:91], v[108:111]
	v_mfma_f32_16x16x32_bf16 v[112:115], v[222:225], v[28:31], v[112:115]
	v_mfma_f32_16x16x32_bf16 v[138:141], v[222:225], v[60:63], v[138:141]
	v_mfma_f32_16x16x32_bf16 v[142:145], v[222:225], v[88:91], v[142:145]
	s_waitcnt lgkmcnt(4)
	v_mfma_f32_16x16x32_bf16 v[100:103], v[210:213], v[32:35], v[100:103]
	v_mfma_f32_16x16x32_bf16 v[104:107], v[210:213], v[64:67], v[104:107]
	v_mfma_f32_16x16x32_bf16 v[112:115], v[226:229], v[32:35], v[112:115]
	v_mfma_f32_16x16x32_bf16 v[138:141], v[226:229], v[64:67], v[138:141]
	ds_read_b128 v[206:209], v130 offset:432
	ds_read_b128 v[222:225], v130 offset:1008
	ds_read_b128 v[210:213], v131 offset:432
	ds_read_b128 v[226:229], v131 offset:1008
	s_waitcnt lgkmcnt(6)
	v_mfma_f32_16x16x32_bf16 v[100:103], v[198:201], v[36:39], v[100:103]
	v_mfma_f32_16x16x32_bf16 v[104:107], v[198:201], v[68:71], v[104:107]
	v_mfma_f32_16x16x32_bf16 v[108:111], v[198:201], v[92:95], v[108:111]
	v_mfma_f32_16x16x32_bf16 v[112:115], v[214:217], v[36:39], v[112:115]
	v_mfma_f32_16x16x32_bf16 v[138:141], v[214:217], v[68:71], v[138:141]
	v_mfma_f32_16x16x32_bf16 v[142:145], v[214:217], v[92:95], v[142:145]
	s_waitcnt lgkmcnt(4)
	v_mfma_f32_16x16x32_bf16 v[100:103], v[202:205], v[40:43], v[100:103]
	v_mfma_f32_16x16x32_bf16 v[104:107], v[202:205], v[72:75], v[104:107]
	v_mfma_f32_16x16x32_bf16 v[112:115], v[218:221], v[40:43], v[112:115]
	v_mfma_f32_16x16x32_bf16 v[138:141], v[218:221], v[72:75], v[138:141]
	s_waitcnt lgkmcnt(2)
	v_mfma_f32_16x16x32_bf16 v[100:103], v[206:209], v[44:47], v[100:103]
	v_mfma_f32_16x16x32_bf16 v[104:107], v[206:209], v[76:79], v[104:107]
	v_mfma_f32_16x16x32_bf16 v[108:111], v[206:209], v[96:99], v[108:111]
	v_mfma_f32_16x16x32_bf16 v[112:115], v[222:225], v[44:47], v[112:115]
	v_mfma_f32_16x16x32_bf16 v[138:141], v[222:225], v[76:79], v[138:141]
	v_mfma_f32_16x16x32_bf16 v[142:145], v[222:225], v[96:99], v[142:145]
	s_waitcnt lgkmcnt(0)
	v_mfma_f32_16x16x32_bf16 v[100:103], v[210:213], v[48:51], v[100:103]
	v_mfma_f32_16x16x32_bf16 v[104:107], v[210:213], v[80:83], v[104:107]
	v_mfma_f32_16x16x32_bf16 v[112:115], v[226:229], v[48:51], v[112:115]
	v_mfma_f32_16x16x32_bf16 v[138:141], v[226:229], v[80:83], v[138:141]
	s_waitcnt lgkmcnt(0)
	s_barrier
	s_waitcnt vmcnt(3)
	ds_write_b128 v134, v[230:233]
	ds_write_b128 v134, v[234:237] offset:4608
	ds_write_b128 v135, v[238:241]
	s_add_i32 s52, s4, 4
	s_min_u32 s52, s52, 31
	s_lshl_b32 s52, s52, 13
	s_add_u32 s26, s50, s52
	s_addc_u32 s27, s51, 0
	global_load_dwordx4 v[230:233], v154, s[26:27]
	global_load_dwordx4 v[234:237], v155, s[26:27]
	global_load_dwordx4 v[238:241], v159, s[26:27]
	v_exp_f32_e32 v198, v100
	v_exp_f32_e32 v199, v101
	v_exp_f32_e32 v200, v102
	v_exp_f32_e32 v201, v103
	v_exp_f32_e32 v202, v112
	v_exp_f32_e32 v203, v113
	v_exp_f32_e32 v204, v114
	v_exp_f32_e32 v205, v115
	v_exp_f32_e32 v214, v104
	v_add_f32_e32 v198, 1.0, v198
	v_exp_f32_e32 v215, v105
	v_add_f32_e32 v199, 1.0, v199
	v_exp_f32_e32 v216, v106
	v_add_f32_e32 v200, 1.0, v200
	v_exp_f32_e32 v217, v107
	v_add_f32_e32 v201, 1.0, v201
	v_exp_f32_e32 v218, v138
	v_add_f32_e32 v202, 1.0, v202
	v_exp_f32_e32 v219, v139
	v_add_f32_e32 v203, 1.0, v203
	v_exp_f32_e32 v220, v140
	v_add_f32_e32 v204, 1.0, v204
	v_exp_f32_e32 v221, v141
	v_add_f32_e32 v205, 1.0, v205
	v_rcp_f32_e32 v198, v198
	v_add_f32_e32 v214, 1.0, v214
	v_rcp_f32_e32 v199, v199
	v_add_f32_e32 v215, 1.0, v215
	v_rcp_f32_e32 v200, v200
	v_add_f32_e32 v216, 1.0, v216
	v_rcp_f32_e32 v201, v201
	v_add_f32_e32 v217, 1.0, v217
	v_rcp_f32_e32 v202, v202
	v_add_f32_e32 v218, 1.0, v218
	v_rcp_f32_e32 v203, v203
	v_add_f32_e32 v219, 1.0, v219
	v_rcp_f32_e32 v204, v204
	v_add_f32_e32 v220, 1.0, v220
	v_rcp_f32_e32 v205, v205
	v_add_f32_e32 v221, 1.0, v221
	v_mul_f32_e32 v198, v179, v198
	v_mul_f32_e32 v199, v179, v199
	v_mul_f32_e32 v200, v179, v200
	v_mul_f32_e32 v201, v179, v201
	v_mul_f32_e32 v202, v179, v202
	v_mul_f32_e32 v203, v179, v203
	v_mul_f32_e32 v204, v179, v204
	v_mul_f32_e32 v205, v179, v205
	v_exp_f32_e32 v120, v198
	v_exp_f32_e32 v121, v199
	v_exp_f32_e32 v122, v200
	v_exp_f32_e32 v123, v201
	v_exp_f32_e32 v124, v202
	v_exp_f32_e32 v125, v203
	v_exp_f32_e32 v126, v204
	v_exp_f32_e32 v127, v205
	v_fma_f32 v206, -v120, v120, 1.0
	v_fma_f32 v207, -v121, v121, 1.0
	v_fma_f32 v208, -v122, v122, 1.0
	v_fma_f32 v209, -v123, v123, 1.0
	v_fma_f32 v210, -v124, v124, 1.0
	v_fma_f32 v211, -v125, v125, 1.0
	v_fma_f32 v212, -v126, v126, 1.0
	v_fma_f32 v213, -v127, v127, 1.0
	v_max_f32_e32 v206, 0xda24260, v206
	v_max_f32_e32 v207, 0xda24260, v207
	v_max_f32_e32 v208, 0xda24260, v208
	v_max_f32_e32 v209, 0xda24260, v209
	v_max_f32_e32 v210, 0xda24260, v210
	v_max_f32_e32 v211, 0xda24260, v211
	v_max_f32_e32 v212, 0xda24260, v212
	v_max_f32_e32 v213, 0xda24260, v213
	v_mul_f32_e32 v198, v214, v206
	v_mul_f32_e32 v199, v215, v207
	v_mul_f32_e32 v200, v216, v208
	v_mul_f32_e32 v201, v217, v209
	v_mul_f32_e32 v202, v218, v210
	v_mul_f32_e32 v203, v219, v211
	v_mul_f32_e32 v204, v220, v212
	v_mul_f32_e32 v205, v221, v213
	v_mul_f32_e32 v214, v214, v198
	v_mul_f32_e32 v215, v215, v199
	v_mul_f32_e32 v216, v216, v200
	v_mul_f32_e32 v217, v217, v201
	v_mul_f32_e32 v218, v218, v202
	v_mul_f32_e32 v219, v219, v203
	v_mul_f32_e32 v220, v220, v204
	v_mul_f32_e32 v221, v221, v205
	v_rsq_f32_e32 v214, v214
	v_mul_f32_e32 v222, v108, v206
	v_rsq_f32_e32 v215, v215
	v_mul_f32_e32 v223, v109, v207
	v_rsq_f32_e32 v216, v216
	v_mul_f32_e32 v224, v110, v208
	v_rsq_f32_e32 v217, v217
	v_mul_f32_e32 v225, v111, v209
	v_rsq_f32_e32 v218, v218
	v_mul_f32_e32 v226, v142, v210
	v_rsq_f32_e32 v219, v219
	v_mul_f32_e32 v227, v143, v211
	v_rsq_f32_e32 v220, v220
	v_mul_f32_e32 v228, v144, v212
	v_rsq_f32_e32 v221, v221
	v_mul_f32_e32 v229, v145, v213
	v_mul_f32_e32 v170, v222, v214
	v_mul_f32_e32 v171, v223, v215
	v_mul_f32_e32 v172, v224, v216
	v_mul_f32_e32 v173, v225, v217
	v_mul_f32_e32 v174, v226, v218
	v_mul_f32_e32 v175, v227, v219
	v_mul_f32_e32 v176, v228, v220
	v_mul_f32_e32 v177, v229, v221
	v_mov_b32_e32 v198, v170
	v_mov_b32_e32 v199, v120
	v_fma_f32 v198, v121, v198, v171
	v_mul_f32_e32 v199, v199, v121
	v_fma_f32 v198, v122, v198, v172
	v_mul_f32_e32 v199, v199, v122
	v_fma_f32 v198, v123, v198, v173
	v_mul_f32_e32 v199, v199, v123
	v_fma_f32 v198, v124, v198, v174
	v_mul_f32_e32 v199, v199, v124
	v_fma_f32 v198, v125, v198, v175
	v_mul_f32_e32 v199, v199, v125
	v_fma_f32 v198, v126, v198, v176
	v_mul_f32_e32 v199, v199, v126
	v_fma_f32 v198, v127, v198, v177
	v_mul_f32_e32 v199, v199, v127
	ds_bpermute_b32 v164, v117, v199 offset:0
	ds_bpermute_b32 v246, v117, v198 offset:0
	ds_bpermute_b32 v165, v117, v199 offset:64
	ds_bpermute_b32 v247, v117, v198 offset:64
	ds_bpermute_b32 v166, v117, v199 offset:128
	ds_bpermute_b32 v248, v117, v198 offset:128
	ds_bpermute_b32 v167, v117, v199 offset:192
	ds_bpermute_b32 v249, v117, v198 offset:192
	s_waitcnt lgkmcnt(0)
	v_mov_b32_e32 v251, v246
	v_mov_b32_e32 v250, v164
	v_fma_f32 v251, v251, v165, v247
	v_mul_f32_e32 v250, v250, v165
	v_fma_f32 v251, v251, v166, v248
	v_mul_f32_e32 v250, v250, v166
	v_fma_f32 v251, v251, v167, v249
	v_mul_f32_e32 v250, v250, v167
	s_mov_b64 exec, s[10:11]
	ds_write_b64 v182, v[250:251] offset:1024
	s_mov_b64 exec, -1
	s_waitcnt lgkmcnt(0)
	s_barrier
	ds_read2_b64 v[4:7], v183 offset0:128 offset1:144
	s_add_i32 s52, s4, 1
	s_lshl_b32 s52, s52, 12
	v_add_u32_e32 v197, s52, v116
	s_waitcnt lgkmcnt(0)
	v_fma_f32 v198, v180, v4, v5
	v_cndmask_b32_e64 v199, v180, v198, s[24:25]
	v_fma_f32 v180, v198, v6, v7
	v_fma_f32 v200, v199, v164, v246
	v_cndmask_b32_e64 v199, v199, v200, s[16:17]
	v_fma_f32 v200, v199, v165, v247
	v_cndmask_b32_e64 v199, v199, v200, s[20:21]
	v_fma_f32 v200, v199, v166, v248
	v_cndmask_b32_e64 v199, v199, v200, s[22:23]
	v_fma_f32 v214, v120, v199, v170
	v_fma_f32 v215, v121, v214, v171
	v_fma_f32 v216, v122, v215, v172
	v_fma_f32 v217, v123, v216, v173
	v_fma_f32 v218, v124, v217, v174
	v_fma_f32 v219, v125, v218, v175
	v_fma_f32 v220, v126, v219, v176
	v_fma_f32 v221, v127, v220, v177
	s_cmp_lt_u32 s4, 16
	s_cbranch_scc1 .Lrec2_rmw_d0_p1_store
	ds_read_u16 v206, v197 offset:0
	ds_read_u16 v207, v197 offset:64
	ds_read_u16 v208, v197 offset:128
	ds_read_u16 v209, v197 offset:192
	ds_read_u16 v210, v197 offset:256
	ds_read_u16 v211, v197 offset:320
	ds_read_u16 v212, v197 offset:384
	ds_read_u16 v213, v197 offset:448
	s_waitcnt lgkmcnt(0)
	v_lshlrev_b32_e32 v206, 16, v206
	v_lshlrev_b32_e32 v207, 16, v207
	v_lshlrev_b32_e32 v208, 16, v208
	v_lshlrev_b32_e32 v209, 16, v209
	v_lshlrev_b32_e32 v210, 16, v210
	v_lshlrev_b32_e32 v211, 16, v211
	v_lshlrev_b32_e32 v212, 16, v212
	v_lshlrev_b32_e32 v213, 16, v213
	v_add_f32_e32 v214, v214, v206
	v_add_f32_e32 v215, v215, v207
	v_add_f32_e32 v216, v216, v208
	v_add_f32_e32 v217, v217, v209
	v_add_f32_e32 v218, v218, v210
	v_add_f32_e32 v219, v219, v211
	v_add_f32_e32 v220, v220, v212
	v_add_f32_e32 v221, v221, v213
.Lrec2_rmw_d0_p1_store:
	v_cvt_pk_bf16_f32 v206, v214, v215
	v_cvt_pk_bf16_f32 v208, v216, v217
	v_cvt_pk_bf16_f32 v210, v218, v219
	v_cvt_pk_bf16_f32 v212, v220, v221
	ds_write_b16 v197, v206 offset:0
	ds_write_b16_d16_hi v197, v206 offset:64
	ds_write_b16 v197, v208 offset:128
	ds_write_b16_d16_hi v197, v208 offset:192
	ds_write_b16 v197, v210 offset:256
	ds_write_b16_d16_hi v197, v210 offset:320
	ds_write_b16 v197, v212 offset:384
	ds_write_b16_d16_hi v197, v212 offset:448
	s_add_i32 s4, s4, 2
	s_cmp_lt_u32 s4, 32
	s_cbranch_scc1 .Lrec2_loop_d0
	s_barrier
	s_branch .Lrec2_done
.Lrec2_bwd:
	v_and_b32_e32 v252, 15, v157
	v_lshrrev_b32_e32 v253, 4, v157
	s_bfe_u32 s5, s85, 0x10006
	s_bfe_u32 s6, s85, 0x10007
	s_and_b32 s8, s84, 1
	v_readlane_b32 s26, v254, 13
	v_readlane_b32 s27, v254, 14
	s_nop 3
	s_lshl_b32 s9, s70, 2
	s_add_i32 s9, s9, 2
	s_lshl_b32 s52, s9, 15
	s_add_u32 s26, s26, 0x100000
	s_addc_u32 s27, s27, 0
	s_add_u32 s26, s26, s52
	s_addc_u32 s27, s27, 0
	v_add_u32_e32 v8, s34, v252
	v_lshlrev_b32_e32 v9, 7, v8
	v_lshl_add_u32 v9, v253, 4, v9
	s_lshl_b32 s64, s8, 6
	s_xor_b32 s71, s64, 64
	v_add_u32_e32 v10, s64, v9
	v_add_u32_e32 v255, s71, v9
	s_add_u32 s38, s26, 0x0
	s_addc_u32 s39, s27, 0
	global_load_dwordx4 v[20:23], v10, s[38:39]
	global_load_dwordx4 v[24:27], v255, s[38:39]
	s_add_u32 s38, s26, 0x2000
	s_addc_u32 s39, s27, 0
	global_load_dwordx4 v[28:31], v10, s[38:39]
	global_load_dwordx4 v[32:35], v255, s[38:39]
	s_add_u32 s38, s26, 0x4000
	s_addc_u32 s39, s27, 0
	global_load_dwordx4 v[36:39], v10, s[38:39]
	global_load_dwordx4 v[40:43], v255, s[38:39]
	s_add_u32 s38, s26, 0x6000
	s_addc_u32 s39, s27, 0
	global_load_dwordx4 v[44:47], v10, s[38:39]
	global_load_dwordx4 v[48:51], v255, s[38:39]
	s_add_u32 s38, s26, 0x8000
	s_addc_u32 s39, s27, 0
	global_load_dwordx4 v[52:55], v10, s[38:39]
	global_load_dwordx4 v[56:59], v255, s[38:39]
	s_add_u32 s38, s26, 0xa000
	s_addc_u32 s39, s27, 0
	global_load_dwordx4 v[60:63], v10, s[38:39]
	global_load_dwordx4 v[64:67], v255, s[38:39]
	s_add_u32 s38, s26, 0xc000
	s_addc_u32 s39, s27, 0
	global_load_dwordx4 v[68:71], v10, s[38:39]
	global_load_dwordx4 v[72:75], v255, s[38:39]
	s_add_u32 s38, s26, 0xe000
	s_addc_u32 s39, s27, 0
	global_load_dwordx4 v[76:79], v10, s[38:39]
	global_load_dwordx4 v[80:83], v255, s[38:39]
	s_lshl_b32 s52, s9, 8
	s_add_i32 s52, s52, 0x15240
	v_lshlrev_b32_e32 v8, 2, v8
	v_add_u32_e32 v9, s52, v8
	global_load_dword v128, v9, s[90:91]
	global_load_dword v178, v9, s[90:91] offset:256
	s_lshl_b32 s52, s70, 8
	s_add_i32 s52, s52, 0x13240
	v_add_u32_e32 v9, s52, v8
	global_load_dword v179, v9, s[90:91]
	v_lshlrev_b32_e32 v198, 3, v253
	v_sub_u32_e32 v198, v252, v198
	v_lshl_add_u32 v198, s6, 4, v198
	v_cmp_gt_u32_e32 vcc, 8, v198
	v_and_b32_e32 v199, 1, v198
	v_lshlrev_b32_e32 v199, 4, v199
	v_lshrrev_b32_e32 v200, 1, v198
	s_nop 1
	v_cndmask_b32_e32 v200, 7, v200, vcc
	v_cmp_eq_u32_e64 s[58:59], 0, v200
	v_cmp_eq_u32_e64 s[60:61], 1, v200
	v_cmp_eq_u32_e64 s[98:99], 2, v200
	v_cmp_eq_u32_e64 s[100:101], 3, v200
	s_nop 1
	v_lshrrev_b32_e32 v201, 16, v184
	v_lshlrev_b32_e32 v201, v199, v201
	v_cndmask_b32_e64 v84, 0, v201, s[58:59]
	v_cndmask_b32_e64 v85, 0, v201, s[60:61]
	v_cndmask_b32_e64 v86, 0, v201, s[98:99]
	v_cndmask_b32_e64 v87, 0, v201, s[100:101]
	v_lshrrev_b32_e32 v201, 16, v185
	v_lshlrev_b32_e32 v201, v199, v201
	v_cndmask_b32_e64 v88, 0, v201, s[58:59]
	v_cndmask_b32_e64 v89, 0, v201, s[60:61]
	v_cndmask_b32_e64 v90, 0, v201, s[98:99]
	v_cndmask_b32_e64 v91, 0, v201, s[100:101]
	v_lshrrev_b32_e32 v201, 16, v195
	v_lshlrev_b32_e32 v201, v199, v201
	v_cndmask_b32_e64 v92, 0, v201, s[58:59]
	v_cndmask_b32_e64 v93, 0, v201, s[60:61]
	v_cndmask_b32_e64 v94, 0, v201, s[98:99]
	v_cndmask_b32_e64 v95, 0, v201, s[100:101]
	v_lshrrev_b32_e32 v201, 16, v197
	v_lshlrev_b32_e32 v201, v199, v201
	v_cndmask_b32_e64 v96, 0, v201, s[58:59]
	v_cndmask_b32_e64 v97, 0, v201, s[60:61]
	v_cndmask_b32_e64 v98, 0, v201, s[98:99]
	v_cndmask_b32_e64 v99, 0, v201, s[100:101]
	v_mov_b32_e32 v184, 1.0
	v_mov_b32_e32 v185, 1.0
	v_lshrrev_b32_e32 v8, 2, v252
	v_and_b32_e32 v9, 3, v252
	v_lshl_add_u32 v8, v8, 3, v9
	v_lshl_add_u32 v8, s5, 5, v8
	v_mul_u32_u24_e32 v8, 0x90, v8
	v_lshl_add_u32 v8, v253, 4, v8
	v_add_u32_e32 v8, 0x22f00, v8
	v_add_u32_e32 v130, s64, v8
	v_add_u32_e32 v131, s71, v8
	v_and_b32_e32 v8, 0xff, v156
	v_lshrrev_b32_e32 v9, 3, v8
	v_mul_u32_u24_e32 v9, 0x90, v9
	v_and_b32_e32 v10, 7, v8
	v_lshl_add_u32 v9, v10, 4, v9
	v_add_u32_e32 v134, 0x22f00, v9
	v_lshlrev_b32_e32 v154, 4, v8
	v_add_u32_e32 v155, 0x1000, v154
	v_min_u32_e32 v9, 23, v8
	v_add_u32_e32 v9, 0x200, v9
	v_lshlrev_b32_e32 v159, 4, v9
	v_lshrrev_b32_e32 v10, 3, v9
	v_mul_u32_u24_e32 v10, 0x90, v10
	v_and_b32_e32 v9, 7, v9
	v_lshl_add_u32 v10, v9, 4, v10
	v_add_u32_e32 v135, 0x22f00, v10
	s_lshl_b32 s52, s6, 8
	s_add_i32 s52, s52, 0x20300
	v_lshl_add_u32 v183, v252, 3, s52
	s_lshl_b32 s52, s5, 7
	v_add_u32_e32 v182, s52, v183
	s_lshl_b32 s52, s5, 11
	s_lshl_b32 s9, s6, 5
	s_add_i32 s52, s52, s9
	s_add_i32 s52, s52, 0x100
	v_lshlrev_b32_e32 v8, 9, v253
	v_lshl_add_u32 v8, v252, 1, v8
	v_add_u32_e32 v116, s52, v8
	v_lshlrev_b32_e32 v117, 2, v252
	v_cmp_eq_u32_e64 s[10:11], 0, v253
	v_cmp_gt_u32_e64 s[16:17], 3, v253
	v_cmp_gt_u32_e64 s[20:21], 2, v253
	v_cmp_gt_u32_e64 s[22:23], 1, v253
	s_cmp_eq_u32 s5, 0
	s_cselect_b64 s[24:25], -1, 0
	v_mov_b32_e32 v180, 0
	s_add_u32 s26, s50, 0x3e000
	s_addc_u32 s27, s51, 0
	global_load_dwordx4 v[230:233], v154, s[26:27]
	global_load_dwordx4 v[234:237], v155, s[26:27]
	global_load_dwordx4 v[238:241], v159, s[26:27]
	s_add_u32 s26, s50, 0x3c000
	s_addc_u32 s27, s51, 0
	global_load_dwordx4 v[146:149], v154, s[26:27]
	global_load_dwordx4 v[150:153], v155, s[26:27]
	global_load_dwordx4 v[160:163], v159, s[26:27]
	s_waitcnt vmcnt(0)
	v_mov_b32_e32 v12, v128
	v_mov_b32_e32 v16, v178
	v_mov_b32_e32 v242, v133
	v_mov_b32_e32 v13, v128
	v_mov_b32_e32 v17, v178
	v_mov_b32_e32 v243, v133
	v_mov_b32_e32 v14, v128
	v_mov_b32_e32 v18, v178
	v_mov_b32_e32 v244, v133
	v_mov_b32_e32 v15, v128
	v_mov_b32_e32 v19, v178
	v_mov_b32_e32 v245, v133
	ds_write_b128 v134, v[230:233]
	ds_write_b128 v134, v[234:237] offset:4608
	ds_write_b128 v135, v[238:241]
	s_add_u32 s26, s50, 0x3a000
	s_addc_u32 s27, s51, 0
	global_load_dwordx4 v[230:233], v154, s[26:27]
	global_load_dwordx4 v[234:237], v155, s[26:27]
	global_load_dwordx4 v[238:241], v159, s[26:27]
	s_mov_b32 s4, 0
	s_waitcnt lgkmcnt(0)
	s_barrier
	s_barrier
.Lrec2_loop_d1:
	ds_read_b128 v[198:201], v130 offset:0
	ds_read_b128 v[214:217], v130 offset:576
	ds_read_b128 v[202:205], v131 offset:0
	ds_read_b128 v[218:221], v131 offset:576
	ds_read_b128 v[206:209], v130 offset:144
	ds_read_b128 v[222:225], v130 offset:720
	ds_read_b128 v[210:213], v131 offset:144
	s_waitcnt lgkmcnt(14)
	ds_read_b128 v[226:229], v131 offset:720
	s_waitcnt lgkmcnt(6)
	v_mfma_f32_16x16x32_bf16 v[100:103], v[198:201], v[20:23], v[12:15]
	v_mfma_f32_16x16x32_bf16 v[104:107], v[198:201], v[52:55], v[16:19]
	v_mfma_f32_16x16x32_bf16 v[108:111], v[198:201], v[84:87], v[242:245]
	v_mfma_f32_16x16x32_bf16 v[112:115], v[214:217], v[20:23], v[12:15]
	v_mfma_f32_16x16x32_bf16 v[138:141], v[214:217], v[52:55], v[16:19]
	v_mfma_f32_16x16x32_bf16 v[142:145], v[214:217], v[84:87], v[242:245]
	s_waitcnt lgkmcnt(4)
	v_mfma_f32_16x16x32_bf16 v[100:103], v[202:205], v[24:27], v[100:103]
	v_mfma_f32_16x16x32_bf16 v[104:107], v[202:205], v[56:59], v[104:107]
	v_mfma_f32_16x16x32_bf16 v[112:115], v[218:221], v[24:27], v[112:115]
	v_mfma_f32_16x16x32_bf16 v[138:141], v[218:221], v[56:59], v[138:141]
	ds_read_b128 v[198:201], v130 offset:288
	ds_read_b128 v[214:217], v130 offset:864
	ds_read_b128 v[202:205], v131 offset:288
	ds_read_b128 v[218:221], v131 offset:864
	s_waitcnt lgkmcnt(6)
	v_mfma_f32_16x16x32_bf16 v[100:103], v[206:209], v[28:31], v[100:103]
	v_mfma_f32_16x16x32_bf16 v[104:107], v[206:209], v[60:63], v[104:107]
	v_mfma_f32_16x16x32_bf16 v[108:111], v[206:209], v[88:91], v[108:111]
	v_mfma_f32_16x16x32_bf16 v[112:115], v[222:225], v[28:31], v[112:115]
	v_mfma_f32_16x16x32_bf16 v[138:141], v[222:225], v[60:63], v[138:141]
	v_mfma_f32_16x16x32_bf16 v[142:145], v[222:225], v[88:91], v[142:145]
	s_waitcnt lgkmcnt(4)
	v_mfma_f32_16x16x32_bf16 v[100:103], v[210:213], v[32:35], v[100:103]
	v_mfma_f32_16x16x32_bf16 v[104:107], v[210:213], v[64:67], v[104:107]
	v_mfma_f32_16x16x32_bf16 v[112:115], v[226:229], v[32:35], v[112:115]
	v_mfma_f32_16x16x32_bf16 v[138:141], v[226:229], v[64:67], v[138:141]
	ds_read_b128 v[206:209], v130 offset:432
	ds_read_b128 v[222:225], v130 offset:1008
	ds_read_b128 v[210:213], v131 offset:432
	ds_read_b128 v[226:229], v131 offset:1008
	s_waitcnt lgkmcnt(6)
	v_mfma_f32_16x16x32_bf16 v[100:103], v[198:201], v[36:39], v[100:103]
	v_mfma_f32_16x16x32_bf16 v[104:107], v[198:201], v[68:71], v[104:107]
	v_mfma_f32_16x16x32_bf16 v[108:111], v[198:201], v[92:95], v[108:111]
	v_mfma_f32_16x16x32_bf16 v[112:115], v[214:217], v[36:39], v[112:115]
	v_mfma_f32_16x16x32_bf16 v[138:141], v[214:217], v[68:71], v[138:141]
	v_mfma_f32_16x16x32_bf16 v[142:145], v[214:217], v[92:95], v[142:145]
	s_waitcnt lgkmcnt(4)
	v_mfma_f32_16x16x32_bf16 v[100:103], v[202:205], v[40:43], v[100:103]
	v_mfma_f32_16x16x32_bf16 v[104:107], v[202:205], v[72:75], v[104:107]
	v_mfma_f32_16x16x32_bf16 v[112:115], v[218:221], v[40:43], v[112:115]
	v_mfma_f32_16x16x32_bf16 v[138:141], v[218:221], v[72:75], v[138:141]
	s_waitcnt lgkmcnt(2)
	v_mfma_f32_16x16x32_bf16 v[100:103], v[206:209], v[44:47], v[100:103]
	v_mfma_f32_16x16x32_bf16 v[104:107], v[206:209], v[76:79], v[104:107]
	v_mfma_f32_16x16x32_bf16 v[108:111], v[206:209], v[96:99], v[108:111]
	v_mfma_f32_16x16x32_bf16 v[112:115], v[222:225], v[44:47], v[112:115]
	v_mfma_f32_16x16x32_bf16 v[138:141], v[222:225], v[76:79], v[138:141]
	v_mfma_f32_16x16x32_bf16 v[142:145], v[222:225], v[96:99], v[142:145]
	s_waitcnt lgkmcnt(0)
	v_mfma_f32_16x16x32_bf16 v[100:103], v[210:213], v[48:51], v[100:103]
	v_mfma_f32_16x16x32_bf16 v[104:107], v[210:213], v[80:83], v[104:107]
	v_mfma_f32_16x16x32_bf16 v[112:115], v[226:229], v[48:51], v[112:115]
	v_mfma_f32_16x16x32_bf16 v[138:141], v[226:229], v[80:83], v[138:141]
	s_waitcnt lgkmcnt(0)
	s_barrier
	s_waitcnt vmcnt(3)
	ds_write_b128 v134, v[146:149]
	ds_write_b128 v134, v[150:153] offset:4608
	ds_write_b128 v135, v[160:163]
	s_add_i32 s52, s4, 3
	s_min_u32 s52, s52, 31
	s_sub_i32 s52, 31, s52
	s_lshl_b32 s52, s52, 13
	s_add_u32 s26, s50, s52
	s_addc_u32 s27, s51, 0
	global_load_dwordx4 v[146:149], v154, s[26:27]
	global_load_dwordx4 v[150:153], v155, s[26:27]
	global_load_dwordx4 v[160:163], v159, s[26:27]
	v_exp_f32_e32 v198, v100
	v_exp_f32_e32 v199, v101
	v_exp_f32_e32 v200, v102
	v_exp_f32_e32 v201, v103
	v_exp_f32_e32 v202, v112
	v_exp_f32_e32 v203, v113
	v_exp_f32_e32 v204, v114
	v_exp_f32_e32 v205, v115
	v_exp_f32_e32 v214, v104
	v_add_f32_e32 v198, 1.0, v198
	v_exp_f32_e32 v215, v105
	v_add_f32_e32 v199, 1.0, v199
	v_exp_f32_e32 v216, v106
	v_add_f32_e32 v200, 1.0, v200
	v_exp_f32_e32 v217, v107
	v_add_f32_e32 v201, 1.0, v201
	v_exp_f32_e32 v218, v138
	v_add_f32_e32 v202, 1.0, v202
	v_exp_f32_e32 v219, v139
	v_add_f32_e32 v203, 1.0, v203
	v_exp_f32_e32 v220, v140
	v_add_f32_e32 v204, 1.0, v204
	v_exp_f32_e32 v221, v141
	v_add_f32_e32 v205, 1.0, v205
	v_rcp_f32_e32 v198, v198
	v_add_f32_e32 v214, 1.0, v214
	v_rcp_f32_e32 v199, v199
	v_add_f32_e32 v215, 1.0, v215
	v_rcp_f32_e32 v200, v200
	v_add_f32_e32 v216, 1.0, v216
	v_rcp_f32_e32 v201, v201
	v_add_f32_e32 v217, 1.0, v217
	v_rcp_f32_e32 v202, v202
	v_add_f32_e32 v218, 1.0, v218
	v_rcp_f32_e32 v203, v203
	v_add_f32_e32 v219, 1.0, v219
	v_rcp_f32_e32 v204, v204
	v_add_f32_e32 v220, 1.0, v220
	v_rcp_f32_e32 v205, v205
	v_add_f32_e32 v221, 1.0, v221
	v_mul_f32_e32 v198, v179, v198
	v_mul_f32_e32 v199, v179, v199
	v_mul_f32_e32 v200, v179, v200
	v_mul_f32_e32 v201, v179, v201
	v_mul_f32_e32 v202, v179, v202
	v_mul_f32_e32 v203, v179, v203
	v_mul_f32_e32 v204, v179, v204
	v_mul_f32_e32 v205, v179, v205
	v_exp_f32_e32 v120, v198
	v_exp_f32_e32 v121, v199
	v_exp_f32_e32 v122, v200
	v_exp_f32_e32 v123, v201
	v_exp_f32_e32 v124, v202
	v_exp_f32_e32 v125, v203
	v_exp_f32_e32 v126, v204
	v_exp_f32_e32 v127, v205
	v_fma_f32 v206, -v120, v120, 1.0
	v_fma_f32 v207, -v121, v121, 1.0
	v_fma_f32 v208, -v122, v122, 1.0
	v_fma_f32 v209, -v123, v123, 1.0
	v_fma_f32 v210, -v124, v124, 1.0
	v_fma_f32 v211, -v125, v125, 1.0
	v_fma_f32 v212, -v126, v126, 1.0
	v_fma_f32 v213, -v127, v127, 1.0
	v_max_f32_e32 v206, 0xda24260, v206
	v_max_f32_e32 v207, 0xda24260, v207
	v_max_f32_e32 v208, 0xda24260, v208
	v_max_f32_e32 v209, 0xda24260, v209
	v_max_f32_e32 v210, 0xda24260, v210
	v_max_f32_e32 v211, 0xda24260, v211
	v_max_f32_e32 v212, 0xda24260, v212
	v_max_f32_e32 v213, 0xda24260, v213
	v_mul_f32_e32 v198, v214, v206
	v_mul_f32_e32 v199, v215, v207
	v_mul_f32_e32 v200, v216, v208
	v_mul_f32_e32 v201, v217, v209
	v_mul_f32_e32 v202, v218, v210
	v_mul_f32_e32 v203, v219, v211
	v_mul_f32_e32 v204, v220, v212
	v_mul_f32_e32 v205, v221, v213
	v_mul_f32_e32 v214, v214, v198
	v_mul_f32_e32 v215, v215, v199
	v_mul_f32_e32 v216, v216, v200
	v_mul_f32_e32 v217, v217, v201
	v_mul_f32_e32 v218, v218, v202
	v_mul_f32_e32 v219, v219, v203
	v_mul_f32_e32 v220, v220, v204
	v_mul_f32_e32 v221, v221, v205
	v_rsq_f32_e32 v214, v214
	v_mul_f32_e32 v222, v108, v206
	v_rsq_f32_e32 v215, v215
	v_mul_f32_e32 v223, v109, v207
	v_rsq_f32_e32 v216, v216
	v_mul_f32_e32 v224, v110, v208
	v_rsq_f32_e32 v217, v217
	v_mul_f32_e32 v225, v111, v209
	v_rsq_f32_e32 v218, v218
	v_mul_f32_e32 v226, v142, v210
	v_rsq_f32_e32 v219, v219
	v_mul_f32_e32 v227, v143, v211
	v_rsq_f32_e32 v220, v220
	v_mul_f32_e32 v228, v144, v212
	v_rsq_f32_e32 v221, v221
	v_mul_f32_e32 v229, v145, v213
	v_mul_f32_e32 v170, v222, v214
	v_mul_f32_e32 v171, v223, v215
	v_mul_f32_e32 v172, v224, v216
	v_mul_f32_e32 v173, v225, v217
	v_mul_f32_e32 v174, v226, v218
	v_mul_f32_e32 v175, v227, v219
	v_mul_f32_e32 v176, v228, v220
	v_mul_f32_e32 v177, v229, v221
	v_mov_b32_e32 v198, v177
	v_mov_b32_e32 v199, v127
	v_fma_f32 v198, v126, v198, v176
	v_mul_f32_e32 v199, v199, v126
	v_fma_f32 v198, v125, v198, v175
	v_mul_f32_e32 v199, v199, v125
	v_fma_f32 v198, v124, v198, v174
	v_mul_f32_e32 v199, v199, v124
	v_fma_f32 v198, v123, v198, v173
	v_mul_f32_e32 v199, v199, v123
	v_fma_f32 v198, v122, v198, v172
	v_mul_f32_e32 v199, v199, v122
	v_fma_f32 v198, v121, v198, v171
	v_mul_f32_e32 v199, v199, v121
	v_fma_f32 v198, v120, v198, v170
	v_mul_f32_e32 v199, v199, v120
	ds_bpermute_b32 v164, v117, v199 offset:0
	ds_bpermute_b32 v246, v117, v198 offset:0
	ds_bpermute_b32 v165, v117, v199 offset:64
	ds_bpermute_b32 v247, v117, v198 offset:64
	ds_bpermute_b32 v166, v117, v199 offset:128
	ds_bpermute_b32 v248, v117, v198 offset:128
	ds_bpermute_b32 v167, v117, v199 offset:192
	ds_bpermute_b32 v249, v117, v198 offset:192
	s_waitcnt lgkmcnt(0)
	v_mov_b32_e32 v251, v249
	v_mov_b32_e32 v250, v167
	v_fma_f32 v251, v251, v166, v248
	v_mul_f32_e32 v250, v250, v166
	v_fma_f32 v251, v251, v165, v247
	v_mul_f32_e32 v250, v250, v165
	v_fma_f32 v251, v251, v164, v246
	v_mul_f32_e32 v250, v250, v164
	s_mov_b64 exec, s[10:11]
	ds_write_b64 v182, v[250:251] offset:0
	s_mov_b64 exec, -1
	s_waitcnt lgkmcnt(0)
	s_barrier
	ds_read2_b64 v[4:7], v183 offset0:0 offset1:16
	s_add_i32 s52, s4, 0
	s_sub_i32 s52, 31, s52
	s_lshl_b32 s52, s52, 12
	v_add_u32_e32 v197, s52, v116
	s_waitcnt lgkmcnt(0)
	v_fma_f32 v198, v180, v6, v7
	v_cndmask_b32_e64 v199, v180, v198, s[24:25]
	v_fma_f32 v180, v198, v4, v5
	v_fma_f32 v200, v199, v167, v249
	v_cndmask_b32_e64 v199, v199, v200, s[16:17]
	v_fma_f32 v200, v199, v166, v248
	v_cndmask_b32_e64 v199, v199, v200, s[20:21]
	v_fma_f32 v200, v199, v165, v247
	v_cndmask_b32_e64 v199, v199, v200, s[22:23]
	v_fma_f32 v221, v127, v199, v177
	v_fma_f32 v220, v126, v221, v176
	v_fma_f32 v219, v125, v220, v175
	v_fma_f32 v218, v124, v219, v174
	v_fma_f32 v217, v123, v218, v173
	v_fma_f32 v216, v122, v217, v172
	v_fma_f32 v215, v121, v216, v171
	v_fma_f32 v214, v120, v215, v170
	s_cmp_lt_u32 s4, 16
	s_cbranch_scc1 .Lrec2_rmw_d1_p0_store
	ds_read_u16 v206, v197 offset:0
	ds_read_u16 v207, v197 offset:64
	ds_read_u16 v208, v197 offset:128
	ds_read_u16 v209, v197 offset:192
	ds_read_u16 v210, v197 offset:256
	ds_read_u16 v211, v197 offset:320
	ds_read_u16 v212, v197 offset:384
	ds_read_u16 v213, v197 offset:448
	s_waitcnt lgkmcnt(0)
	v_lshlrev_b32_e32 v206, 16, v206
	v_lshlrev_b32_e32 v207, 16, v207
	v_lshlrev_b32_e32 v208, 16, v208
	v_lshlrev_b32_e32 v209, 16, v209
	v_lshlrev_b32_e32 v210, 16, v210
	v_lshlrev_b32_e32 v211, 16, v211
	v_lshlrev_b32_e32 v212, 16, v212
	v_lshlrev_b32_e32 v213, 16, v213
	v_add_f32_e32 v214, v214, v206
	v_add_f32_e32 v215, v215, v207
	v_add_f32_e32 v216, v216, v208
	v_add_f32_e32 v217, v217, v209
	v_add_f32_e32 v218, v218, v210
	v_add_f32_e32 v219, v219, v211
	v_add_f32_e32 v220, v220, v212
	v_add_f32_e32 v221, v221, v213
.Lrec2_rmw_d1_p0_store:
	v_cvt_pk_bf16_f32 v206, v214, v215
	v_cvt_pk_bf16_f32 v208, v216, v217
	v_cvt_pk_bf16_f32 v210, v218, v219
	v_cvt_pk_bf16_f32 v212, v220, v221
	ds_write_b16 v197, v206 offset:0
	ds_write_b16_d16_hi v197, v206 offset:64
	ds_write_b16 v197, v208 offset:128
	ds_write_b16_d16_hi v197, v208 offset:192
	ds_write_b16 v197, v210 offset:256
	ds_write_b16_d16_hi v197, v210 offset:320
	ds_write_b16 v197, v212 offset:384
	ds_write_b16_d16_hi v197, v212 offset:448
	ds_read_b128 v[198:201], v130 offset:0
	ds_read_b128 v[214:217], v130 offset:576
	ds_read_b128 v[202:205], v131 offset:0
	ds_read_b128 v[218:221], v131 offset:576
	ds_read_b128 v[206:209], v130 offset:144
	ds_read_b128 v[222:225], v130 offset:720
	ds_read_b128 v[210:213], v131 offset:144
	s_waitcnt lgkmcnt(14)
	ds_read_b128 v[226:229], v131 offset:720
	s_waitcnt lgkmcnt(6)
	v_mfma_f32_16x16x32_bf16 v[100:103], v[198:201], v[20:23], v[12:15]
	v_mfma_f32_16x16x32_bf16 v[104:107], v[198:201], v[52:55], v[16:19]
	v_mfma_f32_16x16x32_bf16 v[108:111], v[198:201], v[84:87], v[242:245]
	v_mfma_f32_16x16x32_bf16 v[112:115], v[214:217], v[20:23], v[12:15]
	v_mfma_f32_16x16x32_bf16 v[138:141], v[214:217], v[52:55], v[16:19]
	v_mfma_f32_16x16x32_bf16 v[142:145], v[214:217], v[84:87], v[242:245]
	s_waitcnt lgkmcnt(4)
	v_mfma_f32_16x16x32_bf16 v[100:103], v[202:205], v[24:27], v[100:103]
	v_mfma_f32_16x16x32_bf16 v[104:107], v[202:205], v[56:59], v[104:107]
	v_mfma_f32_16x16x32_bf16 v[112:115], v[218:221], v[24:27], v[112:115]
	v_mfma_f32_16x16x32_bf16 v[138:141], v[218:221], v[56:59], v[138:141]
	ds_read_b128 v[198:201], v130 offset:288
	ds_read_b128 v[214:217], v130 offset:864
	ds_read_b128 v[202:205], v131 offset:288
	ds_read_b128 v[218:221], v131 offset:864
	s_waitcnt lgkmcnt(6)
	v_mfma_f32_16x16x32_bf16 v[100:103], v[206:209], v[28:31], v[100:103]
	v_mfma_f32_16x16x32_bf16 v[104:107], v[206:209], v[60:63], v[104:107]
	v_mfma_f32_16x16x32_bf16 v[108:111], v[206:209], v[88:91], v[108:111]
	v_mfma_f32_16x16x32_bf16 v[112:115], v[222:225], v[28:31], v[112:115]
	v_mfma_f32_16x16x32_bf16 v[138:141], v[222:225], v[60:63], v[138:141]
	v_mfma_f32_16x16x32_bf16 v[142:145], v[222:225], v[88:91], v[142:145]
	s_waitcnt lgkmcnt(4)
	v_mfma_f32_16x16x32_bf16 v[100:103], v[210:213], v[32:35], v[100:103]
	v_mfma_f32_16x16x32_bf16 v[104:107], v[210:213], v[64:67], v[104:107]
	v_mfma_f32_16x16x32_bf16 v[112:115], v[226:229], v[32:35], v[112:115]
	v_mfma_f32_16x16x32_bf16 v[138:141], v[226:229], v[64:67], v[138:141]
	ds_read_b128 v[206:209], v130 offset:432
	ds_read_b128 v[222:225], v130 offset:1008
	ds_read_b128 v[210:213], v131 offset:432
	ds_read_b128 v[226:229], v131 offset:1008
	s_waitcnt lgkmcnt(6)
	v_mfma_f32_16x16x32_bf16 v[100:103], v[198:201], v[36:39], v[100:103]
	v_mfma_f32_16x16x32_bf16 v[104:107], v[198:201], v[68:71], v[104:107]
	v_mfma_f32_16x16x32_bf16 v[108:111], v[198:201], v[92:95], v[108:111]
	v_mfma_f32_16x16x32_bf16 v[112:115], v[214:217], v[36:39], v[112:115]
	v_mfma_f32_16x16x32_bf16 v[138:141], v[214:217], v[68:71], v[138:141]
	v_mfma_f32_16x16x32_bf16 v[142:145], v[214:217], v[92:95], v[142:145]
	s_waitcnt lgkmcnt(4)
	v_mfma_f32_16x16x32_bf16 v[100:103], v[202:205], v[40:43], v[100:103]
	v_mfma_f32_16x16x32_bf16 v[104:107], v[202:205], v[72:75], v[104:107]
	v_mfma_f32_16x16x32_bf16 v[112:115], v[218:221], v[40:43], v[112:115]
	v_mfma_f32_16x16x32_bf16 v[138:141], v[218:221], v[72:75], v[138:141]
	s_waitcnt lgkmcnt(2)
	v_mfma_f32_16x16x32_bf16 v[100:103], v[206:209], v[44:47], v[100:103]
	v_mfma_f32_16x16x32_bf16 v[104:107], v[206:209], v[76:79], v[104:107]
	v_mfma_f32_16x16x32_bf16 v[108:111], v[206:209], v[96:99], v[108:111]
	v_mfma_f32_16x16x32_bf16 v[112:115], v[222:225], v[44:47], v[112:115]
	v_mfma_f32_16x16x32_bf16 v[138:141], v[222:225], v[76:79], v[138:141]
	v_mfma_f32_16x16x32_bf16 v[142:145], v[222:225], v[96:99], v[142:145]
	s_waitcnt lgkmcnt(0)
	v_mfma_f32_16x16x32_bf16 v[100:103], v[210:213], v[48:51], v[100:103]
	v_mfma_f32_16x16x32_bf16 v[104:107], v[210:213], v[80:83], v[104:107]
	v_mfma_f32_16x16x32_bf16 v[112:115], v[226:229], v[48:51], v[112:115]
	v_mfma_f32_16x16x32_bf16 v[138:141], v[226:229], v[80:83], v[138:141]
	s_waitcnt lgkmcnt(0)
	s_barrier
	s_waitcnt vmcnt(3)
	ds_write_b128 v134, v[230:233]
	ds_write_b128 v134, v[234:237] offset:4608
	ds_write_b128 v135, v[238:241]
	s_add_i32 s52, s4, 4
	s_min_u32 s52, s52, 31
	s_sub_i32 s52, 31, s52
	s_lshl_b32 s52, s52, 13
	s_add_u32 s26, s50, s52
	s_addc_u32 s27, s51, 0
	global_load_dwordx4 v[230:233], v154, s[26:27]
	global_load_dwordx4 v[234:237], v155, s[26:27]
	global_load_dwordx4 v[238:241], v159, s[26:27]
	v_exp_f32_e32 v198, v100
	v_exp_f32_e32 v199, v101
	v_exp_f32_e32 v200, v102
	v_exp_f32_e32 v201, v103
	v_exp_f32_e32 v202, v112
	v_exp_f32_e32 v203, v113
	v_exp_f32_e32 v204, v114
	v_exp_f32_e32 v205, v115
	v_exp_f32_e32 v214, v104
	v_add_f32_e32 v198, 1.0, v198
	v_exp_f32_e32 v215, v105
	v_add_f32_e32 v199, 1.0, v199
	v_exp_f32_e32 v216, v106
	v_add_f32_e32 v200, 1.0, v200
	v_exp_f32_e32 v217, v107
	v_add_f32_e32 v201, 1.0, v201
	v_exp_f32_e32 v218, v138
	v_add_f32_e32 v202, 1.0, v202
	v_exp_f32_e32 v219, v139
	v_add_f32_e32 v203, 1.0, v203
	v_exp_f32_e32 v220, v140
	v_add_f32_e32 v204, 1.0, v204
	v_exp_f32_e32 v221, v141
	v_add_f32_e32 v205, 1.0, v205
	v_rcp_f32_e32 v198, v198
	v_add_f32_e32 v214, 1.0, v214
	v_rcp_f32_e32 v199, v199
	v_add_f32_e32 v215, 1.0, v215
	v_rcp_f32_e32 v200, v200
	v_add_f32_e32 v216, 1.0, v216
	v_rcp_f32_e32 v201, v201
	v_add_f32_e32 v217, 1.0, v217
	v_rcp_f32_e32 v202, v202
	v_add_f32_e32 v218, 1.0, v218
	v_rcp_f32_e32 v203, v203
	v_add_f32_e32 v219, 1.0, v219
	v_rcp_f32_e32 v204, v204
	v_add_f32_e32 v220, 1.0, v220
	v_rcp_f32_e32 v205, v205
	v_add_f32_e32 v221, 1.0, v221
	v_mul_f32_e32 v198, v179, v198
	v_mul_f32_e32 v199, v179, v199
	v_mul_f32_e32 v200, v179, v200
	v_mul_f32_e32 v201, v179, v201
	v_mul_f32_e32 v202, v179, v202
	v_mul_f32_e32 v203, v179, v203
	v_mul_f32_e32 v204, v179, v204
	v_mul_f32_e32 v205, v179, v205
	v_exp_f32_e32 v120, v198
	v_exp_f32_e32 v121, v199
	v_exp_f32_e32 v122, v200
	v_exp_f32_e32 v123, v201
	v_exp_f32_e32 v124, v202
	v_exp_f32_e32 v125, v203
	v_exp_f32_e32 v126, v204
	v_exp_f32_e32 v127, v205
	v_fma_f32 v206, -v120, v120, 1.0
	v_fma_f32 v207, -v121, v121, 1.0
	v_fma_f32 v208, -v122, v122, 1.0
	v_fma_f32 v209, -v123, v123, 1.0
	v_fma_f32 v210, -v124, v124, 1.0
	v_fma_f32 v211, -v125, v125, 1.0
	v_fma_f32 v212, -v126, v126, 1.0
	v_fma_f32 v213, -v127, v127, 1.0
	v_max_f32_e32 v206, 0xda24260, v206
	v_max_f32_e32 v207, 0xda24260, v207
	v_max_f32_e32 v208, 0xda24260, v208
	v_max_f32_e32 v209, 0xda24260, v209
	v_max_f32_e32 v210, 0xda24260, v210
	v_max_f32_e32 v211, 0xda24260, v211
	v_max_f32_e32 v212, 0xda24260, v212
	v_max_f32_e32 v213, 0xda24260, v213
	v_mul_f32_e32 v198, v214, v206
	v_mul_f32_e32 v199, v215, v207
	v_mul_f32_e32 v200, v216, v208
	v_mul_f32_e32 v201, v217, v209
	v_mul_f32_e32 v202, v218, v210
	v_mul_f32_e32 v203, v219, v211
	v_mul_f32_e32 v204, v220, v212
	v_mul_f32_e32 v205, v221, v213
	v_mul_f32_e32 v214, v214, v198
	v_mul_f32_e32 v215, v215, v199
	v_mul_f32_e32 v216, v216, v200
	v_mul_f32_e32 v217, v217, v201
	v_mul_f32_e32 v218, v218, v202
	v_mul_f32_e32 v219, v219, v203
	v_mul_f32_e32 v220, v220, v204
	v_mul_f32_e32 v221, v221, v205
	v_rsq_f32_e32 v214, v214
	v_mul_f32_e32 v222, v108, v206
	v_rsq_f32_e32 v215, v215
	v_mul_f32_e32 v223, v109, v207
	v_rsq_f32_e32 v216, v216
	v_mul_f32_e32 v224, v110, v208
	v_rsq_f32_e32 v217, v217
	v_mul_f32_e32 v225, v111, v209
	v_rsq_f32_e32 v218, v218
	v_mul_f32_e32 v226, v142, v210
	v_rsq_f32_e32 v219, v219
	v_mul_f32_e32 v227, v143, v211
	v_rsq_f32_e32 v220, v220
	v_mul_f32_e32 v228, v144, v212
	v_rsq_f32_e32 v221, v221
	v_mul_f32_e32 v229, v145, v213
	v_mul_f32_e32 v170, v222, v214
	v_mul_f32_e32 v171, v223, v215
	v_mul_f32_e32 v172, v224, v216
	v_mul_f32_e32 v173, v225, v217
	v_mul_f32_e32 v174, v226, v218
	v_mul_f32_e32 v175, v227, v219
	v_mul_f32_e32 v176, v228, v220
	v_mul_f32_e32 v177, v229, v221
	v_mov_b32_e32 v198, v177
	v_mov_b32_e32 v199, v127
	v_fma_f32 v198, v126, v198, v176
	v_mul_f32_e32 v199, v199, v126
	v_fma_f32 v198, v125, v198, v175
	v_mul_f32_e32 v199, v199, v125
	v_fma_f32 v198, v124, v198, v174
	v_mul_f32_e32 v199, v199, v124
	v_fma_f32 v198, v123, v198, v173
	v_mul_f32_e32 v199, v199, v123
	v_fma_f32 v198, v122, v198, v172
	v_mul_f32_e32 v199, v199, v122
	v_fma_f32 v198, v121, v198, v171
	v_mul_f32_e32 v199, v199, v121
	v_fma_f32 v198, v120, v198, v170
	v_mul_f32_e32 v199, v199, v120
	ds_bpermute_b32 v164, v117, v199 offset:0
	ds_bpermute_b32 v246, v117, v198 offset:0
	ds_bpermute_b32 v165, v117, v199 offset:64
	ds_bpermute_b32 v247, v117, v198 offset:64
	ds_bpermute_b32 v166, v117, v199 offset:128
	ds_bpermute_b32 v248, v117, v198 offset:128
	ds_bpermute_b32 v167, v117, v199 offset:192
	ds_bpermute_b32 v249, v117, v198 offset:192
	s_waitcnt lgkmcnt(0)
	v_mov_b32_e32 v251, v249
	v_mov_b32_e32 v250, v167
	v_fma_f32 v251, v251, v166, v248
	v_mul_f32_e32 v250, v250, v166
	v_fma_f32 v251, v251, v165, v247
	v_mul_f32_e32 v250, v250, v165
	v_fma_f32 v251, v251, v164, v246
	v_mul_f32_e32 v250, v250, v164
	s_mov_b64 exec, s[10:11]
	ds_write_b64 v182, v[250:251] offset:1024
	s_mov_b64 exec, -1
	s_waitcnt lgkmcnt(0)
	s_barrier
	ds_read2_b64 v[4:7], v183 offset0:128 offset1:144
	s_add_i32 s52, s4, 1
	s_sub_i32 s52, 31, s52
	s_lshl_b32 s52, s52, 12
	v_add_u32_e32 v197, s52, v116
	s_waitcnt lgkmcnt(0)
	v_fma_f32 v198, v180, v6, v7
	v_cndmask_b32_e64 v199, v180, v198, s[24:25]
	v_fma_f32 v180, v198, v4, v5
	v_fma_f32 v200, v199, v167, v249
	v_cndmask_b32_e64 v199, v199, v200, s[16:17]
	v_fma_f32 v200, v199, v166, v248
	v_cndmask_b32_e64 v199, v199, v200, s[20:21]
	v_fma_f32 v200, v199, v165, v247
	v_cndmask_b32_e64 v199, v199, v200, s[22:23]
	v_fma_f32 v221, v127, v199, v177
	v_fma_f32 v220, v126, v221, v176
	v_fma_f32 v219, v125, v220, v175
	v_fma_f32 v218, v124, v219, v174
	v_fma_f32 v217, v123, v218, v173
	v_fma_f32 v216, v122, v217, v172
	v_fma_f32 v215, v121, v216, v171
	v_fma_f32 v214, v120, v215, v170
	s_cmp_lt_u32 s4, 16
	s_cbranch_scc1 .Lrec2_rmw_d1_p1_store
	ds_read_u16 v206, v197 offset:0
	ds_read_u16 v207, v197 offset:64
	ds_read_u16 v208, v197 offset:128
	ds_read_u16 v209, v197 offset:192
	ds_read_u16 v210, v197 offset:256
	ds_read_u16 v211, v197 offset:320
	ds_read_u16 v212, v197 offset:384
	ds_read_u16 v213, v197 offset:448
	s_waitcnt lgkmcnt(0)
	v_lshlrev_b32_e32 v206, 16, v206
	v_lshlrev_b32_e32 v207, 16, v207
	v_lshlrev_b32_e32 v208, 16, v208
	v_lshlrev_b32_e32 v209, 16, v209
	v_lshlrev_b32_e32 v210, 16, v210
	v_lshlrev_b32_e32 v211, 16, v211
	v_lshlrev_b32_e32 v212, 16, v212
	v_lshlrev_b32_e32 v213, 16, v213
	v_add_f32_e32 v214, v214, v206
	v_add_f32_e32 v215, v215, v207
	v_add_f32_e32 v216, v216, v208
	v_add_f32_e32 v217, v217, v209
	v_add_f32_e32 v218, v218, v210
	v_add_f32_e32 v219, v219, v211
	v_add_f32_e32 v220, v220, v212
	v_add_f32_e32 v221, v221, v213
.Lrec2_rmw_d1_p1_store:
	v_cvt_pk_bf16_f32 v206, v214, v215
	v_cvt_pk_bf16_f32 v208, v216, v217
	v_cvt_pk_bf16_f32 v210, v218, v219
	v_cvt_pk_bf16_f32 v212, v220, v221
	ds_write_b16 v197, v206 offset:0
	ds_write_b16_d16_hi v197, v206 offset:64
	ds_write_b16 v197, v208 offset:128
	ds_write_b16_d16_hi v197, v208 offset:192
	ds_write_b16 v197, v210 offset:256
	ds_write_b16_d16_hi v197, v210 offset:320
	ds_write_b16 v197, v212 offset:384
	ds_write_b16_d16_hi v197, v212 offset:448
	s_add_i32 s4, s4, 2
	s_cmp_lt_u32 s4, 32
	s_cbranch_scc1 .Lrec2_loop_d1
